# static s_setprio 1 for waves 4-7 across the attention phases (compress/dilated/NSA/MoBA), reset by the next GEMM loop
# baseline (speedup 1.0000x reference)
.LBB0_497:
	v_mov_b32_e32 v4, 0x5000
	global_load_dword v5, v4, s[80:81] sc1
	v_mov_b32_e32 v4, 0x23fd4
	s_waitcnt vmcnt(0)
	ds_write_b32 v4, v5
	s_waitcnt lgkmcnt(0)
	s_xor_b64 s[2:3], s[2:3], -1
	v_writelane_b32 v255, s2, 23
	s_nop 1
	v_writelane_b32 v255, s3, 24
	v_readlane_b32 s2, v254, 0
	s_cmp_le_i32 s2, s1
	s_cselect_b64 s[2:3], -1, 0
	s_cmp_lt_i32 s1, s84
	s_cselect_b64 s[4:5], -1, 0
	s_and_b64 s[2:3], s[2:3], s[4:5]
	s_andn2_b64 vcc, exec, s[2:3]
	s_cbranch_vccnz .LBB0_719
	v_readfirstlane_b32 s2, v210
	s_nop 3
	s_lshr_b32 s2, s2, 6
	s_cmp_ge_u32 s2, 4
	s_cbranch_scc0 .Lprio_att_done
	s_setprio 1
.Lprio_att_done:
	v_readlane_b32 s2, v254, 5
	v_readlane_b32 s3, v254, 6
	s_mov_b32 s1, s79
	s_load_dwordx2 s[46:47], s[2:3], 0x90
	s_waitcnt lgkmcnt(0)
	s_add_u32 s28, s46, 0x15100000
	s_addc_u32 s29, s47, 0
	s_cmp_lt_i32 s1, 64
	s_cbranch_scc0 .LBB0_513
	v_readlane_b32 s2, v255, 21
	s_lshl_b32 s7, s2, 1
	s_add_u32 s8, s46, 0x13000000
	s_addc_u32 s9, s47, 0
	s_add_u32 s2, s46, 0x180000
	s_addc_u32 s3, s47, 0
	s_bitcmp1_b32 s1, 0
	s_cselect_b64 s[18:19], -1, 0
	s_mov_b32 s13, s1
	s_branch .LBB0_501
